# MLA: next-stage K/V LDS staging writes moved into the middle of the stage, first K-fragment reads issued immediately after the stage barrier
# speedup vs baseline: 1.0180x; 1.0180x over previous
; __device__ __forceinline__ unsigned pk2(float lo, float hi) { f32x2_t v = {lo, hi}; bf16x2_t b = __builtin_convertvector(v, bf16x2_t); return __builtin_bit_cast(unsigned, b); }
; #define MFMA32(a, b, c) __builtin_amdgcn_mfma_f32_32x32x16_bf16((a), (b), (c), 0, 0, 0)
; template <bool MASK> __device__ __forceinline__ void sm_iter(int var, SmState& st, const bf16x8 (&qr)[6], const LAS unsigned char* kb, const LAS unsigned char* vb, LAS float* wsf, int kv0, int qpos, int q32, int hi) {
;     ...
; #pragma unroll
;     for (int j = 0; j < 4; ++j) {
;         u32x4 pw;
;         if (j < 2) { const int r0 = 8 * (j & 1); pw.x = pk2(p0[r0], p0[r0 + 1]); pw.y = pk2(p0[r0 + 2], p0[r0 + 3]); pw.z = pk2(p0[r0 + 4], p0[r0 + 5]); pw.w = pk2(p0[r0 + 6], p0[r0 + 7]); }
;         else { const int r0 = 8 * (j & 1); pw.x = pk2(p1[r0], p1[r0 + 1]); pw.y = pk2(p1[r0 + 2], p1[r0 + 3]); pw.z = pk2(p1[r0 + 4], p1[r0 + 5]); pw.w = pk2(p1[r0 + 6], p1[r0 + 7]); }
;         const bf16x8 pa = __builtin_bit_cast(bf16x8, pw);
;         { const s16x4 lo = vlo[2 * j], hh = vhh[2 * j]; const bf16x8 vf = {lo[0], lo[1], lo[2], lo[3], hh[0], hh[1], hh[2], hh[3]}; st.o0 = MFMA32(pa, vf, st.o0); }
;         { const s16x4 lo = vlo[2 * j + 1], hh = vhh[2 * j + 1]; const bf16x8 vf = {lo[0], lo[1], lo[2], lo[3], hh[0], hh[1], hh[2], hh[3]}; st.o1 = MFMA32(pa, vf, st.o1); }
;     }
.Lm3_ok3:
	s_xor_b32 s20, s43, 1
	s_mul_i32 s21, s20, 0x6800
	s_add_i32 s21, s21, 0
	s_mulk_i32 s20, 0x4200
	v_add_u32_e32 v226, s21, v150
	s_waitcnt vmcnt(4)
	ds_write_b128 v226, v[6:9]
	s_waitcnt vmcnt(3)
	ds_write_b128 v226, v[2:5] offset:13312
	v_add_u32_e32 v226, s21, v152
	s_waitcnt vmcnt(0)
	ds_write_b128 v226, v[112:115] offset:128
	v_add_u32_e32 v226, s20, v151
	v_add_u32_e32 v227, 0xd000, v226
	v_add_u32_e32 v226, 0xd080, v226
	ds_write2_b64 v227, v[10:11], v[12:13] offset1:1
	ds_write2_b64 v226, v[108:109], v[110:111] offset1:1
	v_exp_f32_e32 v64, v64
	v_exp_f32_e32 v65, v65
	v_exp_f32_e32 v66, v66
	s_waitcnt lgkmcnt(14)
	v_mfma_f32_32x32x16_bf16 v[48:63], v[116:119], v[84:87], v[198:213]
	v_add_f32_e32 v15, v64, v65
	v_exp_f32_e32 v67, v67
	v_cvt_pk_bf16_f32 v214, v64, v65
	v_exp_f32_e32 v68, v68
	v_add_f32_e32 v177, v66, v67
	v_exp_f32_e32 v69, v69
	v_cvt_pk_bf16_f32 v215, v66, v67
	s_waitcnt lgkmcnt(13)
	v_mfma_f32_32x32x16_bf16 v[48:63], v[120:123], v[88:91], v[48:63]
	v_exp_f32_e32 v70, v70
	v_add_f32_e32 v15, v15, v68
	v_exp_f32_e32 v71, v71
	v_add_f32_e32 v177, v177, v69
	v_exp_f32_e32 v72, v72
	v_cvt_pk_bf16_f32 v216, v68, v69
	s_waitcnt lgkmcnt(12)
	v_mfma_f32_32x32x16_bf16 v[48:63], v[124:127], v[92:95], v[48:63]
	v_exp_f32_e32 v73, v73
	v_add_f32_e32 v15, v15, v70
	v_exp_f32_e32 v74, v74
	v_add_f32_e32 v177, v177, v71
	v_exp_f32_e32 v75, v75
	v_cvt_pk_bf16_f32 v217, v70, v71
	s_waitcnt lgkmcnt(11)
	v_mfma_f32_32x32x16_bf16 v[48:63], v[128:131], v[96:99], v[48:63]
	v_exp_f32_e32 v76, v76
	v_add_f32_e32 v15, v15, v72
	v_exp_f32_e32 v77, v77
	v_add_f32_e32 v177, v177, v73
	v_exp_f32_e32 v78, v78
	v_cvt_pk_bf16_f32 v218, v72, v73
	s_waitcnt lgkmcnt(10)
	v_mfma_f32_32x32x16_bf16 v[48:63], v[132:135], v[100:103], v[48:63]
	v_exp_f32_e32 v79, v79
	v_add_f32_e32 v15, v15, v74
	v_add_f32_e32 v177, v177, v75
	v_cvt_pk_bf16_f32 v219, v74, v75
	v_add_f32_e32 v15, v15, v76
	v_add_f32_e32 v177, v177, v77
	s_waitcnt lgkmcnt(9)
	v_mfma_f32_32x32x16_bf16 v[48:63], v[136:139], v[104:107], v[48:63]
	v_cvt_pk_bf16_f32 v220, v76, v77
	v_add_f32_e32 v15, v15, v78
	v_add_f32_e32 v177, v177, v79
	v_cvt_pk_bf16_f32 v221, v78, v79
	v_add_f32_e32 v15, v15, v177
	v_add_f32_e32 v170, v170, v15
	s_waitcnt lgkmcnt(0)
	v_mfma_f32_32x32x16_bf16 v[16:31], v[214:217], v[140:143], v[16:31]
	ds_read2_b64 v[140:143], v14 offset0:24 offset1:26
	v_mfma_f32_32x32x16_bf16 v[32:47], v[214:217], v[144:147], v[32:47]
	ds_read2_b64 v[144:147], v176 offset0:56 offset1:58
	v_mfma_f32_32x32x16_bf16 v[16:31], v[218:221], v[180:183], v[16:31]
	ds_read2_b64 v[180:183], v14 offset0:28 offset1:30
	v_mfma_f32_32x32x16_bf16 v[32:47], v[218:221], v[184:187], v[32:47]
	ds_read2_b64 v[184:187], v176 offset0:60 offset1:62
	s_nop 3
	v_max3_f32 v15, v48, v49, v50
	v_max3_f32 v177, v51, v52, v53
	v_max3_f32 v15, v15, v54, v55
	v_max3_f32 v177, v177, v56, v57
	v_max3_f32 v15, v15, v58, v59
	v_max3_f32 v177, v177, v60, v61
	v_max3_f32 v15, v15, v62, v63
	v_max_f32_e32 v15, v15, v177
	v_mov_b32_e32 v177, v15
	v_mov_b32_e32 v178, v15
	s_nop 1
	v_permlane32_swap_b32_e32 v177, v178
	v_max3_f32 v15, v15, v177, v178
	v_cmp_gt_f32_e32 vcc, v15, v197
	s_cbranch_vccz .Lm3_ok4
	v_max_f32_e32 v15, v171, v15
	v_sub_f32_e32 v177, v171, v15
	v_exp_f32_e32 v177, v177
	v_sub_f32_e32 v198, v198, v15
	s_and_saveexec_b64 s[20:21], s[40:41]
	ds_write_b32 v149, v177
	s_or_b64 exec, exec, s[20:21]
	v_mul_f32_e32 v170, v170, v177
	v_add_u32_e32 v178, s25, v148
	s_waitcnt lgkmcnt(0)
	ds_read_b128 v[188:191], v178
	ds_read_b128 v[192:195], v178 offset:32
	ds_read_b128 v[222:225], v178 offset:64
	ds_read_b128 v[236:239], v178 offset:96
	v_sub_f32_e32 v48, v48, v15
	v_sub_f32_e32 v49, v49, v15
	v_sub_f32_e32 v50, v50, v15
	v_sub_f32_e32 v51, v51, v15
	v_sub_f32_e32 v52, v52, v15
	v_sub_f32_e32 v53, v53, v15
	v_sub_f32_e32 v54, v54, v15
	v_sub_f32_e32 v55, v55, v15
	v_sub_f32_e32 v56, v56, v15
	v_sub_f32_e32 v57, v57, v15
	v_sub_f32_e32 v58, v58, v15
	v_sub_f32_e32 v59, v59, v15
	v_sub_f32_e32 v60, v60, v15
	v_sub_f32_e32 v61, v61, v15
	v_sub_f32_e32 v62, v62, v15
	v_sub_f32_e32 v63, v63, v15
	v_mov_b32_e32 v199, v198
	v_mov_b32_e32 v200, v198
	v_mov_b32_e32 v201, v198
	v_mov_b32_e32 v202, v198
	v_mov_b32_e32 v203, v198
	v_mov_b32_e32 v204, v198
	v_mov_b32_e32 v205, v198
	v_mov_b32_e32 v206, v198
	v_mov_b32_e32 v207, v198
	v_mov_b32_e32 v208, v198
	v_mov_b32_e32 v209, v198
	v_mov_b32_e32 v210, v198
	v_mov_b32_e32 v211, v198
	v_mov_b32_e32 v212, v198
	v_mov_b32_e32 v213, v198
	v_mov_b32_e32 v171, 0
	v_mov_b32_e32 v197, 0x41000000
	s_nop 11
	s_nop 3
	s_waitcnt lgkmcnt(0)
	v_pk_mul_f32 v[16:17], v[16:17], v[188:189]
	v_pk_mul_f32 v[32:33], v[32:33], v[188:189]
	v_pk_mul_f32 v[18:19], v[18:19], v[190:191]
	v_pk_mul_f32 v[34:35], v[34:35], v[190:191]
	v_pk_mul_f32 v[20:21], v[20:21], v[192:193]
	v_pk_mul_f32 v[36:37], v[36:37], v[192:193]
	v_pk_mul_f32 v[22:23], v[22:23], v[194:195]
	v_pk_mul_f32 v[38:39], v[38:39], v[194:195]
	v_pk_mul_f32 v[24:25], v[24:25], v[222:223]
	v_pk_mul_f32 v[40:41], v[40:41], v[222:223]
	v_pk_mul_f32 v[26:27], v[26:27], v[224:225]
	v_pk_mul_f32 v[42:43], v[42:43], v[224:225]
	v_pk_mul_f32 v[28:29], v[28:29], v[236:237]
	v_pk_mul_f32 v[44:45], v[44:45], v[236:237]
	v_pk_mul_f32 v[30:31], v[30:31], v[238:239]
	v_pk_mul_f32 v[46:47], v[46:47], v[238:239]
; #define SM_LOAD(js) do { kreg0 = *(const u32x4*)(kg + (long)(js) * 128 * ldk); kreg1 = *(const u32x4*)(kg + ((long)(js) * 128 + 64) * ldk); vreg0 = *(const u32x4*)(vg + (js) * 128); vreg1 = *(const u32x4*)(vg + (js) * 128 + 64); \
;         k2reg = *(const u32x4*)(k2g + (long)(js) * 128 * 32); } while (0)
; __device__ __forceinline__ void attn_unit_sm(int b, int h, int qb, const bf16_t* __restrict__ Q, const bf16_t* __restrict__ K, const bf16_t* __restrict__ K2, const bf16_t* __restrict__ Vt, bf16_t* __restrict__ O, const float* __restrict__ cs, LAS unsigned char* lds, int var) {
;     ...
;     for (; it < ns - 2; ++it) {
;         const int cur = it & 1;
;         if (var != 2) SM_LOAD(it + 1);
; #pragma unroll
;         for (int sub = 0; sub < 2; ++sub)
;             sm_iter<false>(var, st, qr, lds + OFF_K + cur * KBUF + (sub * 64 + q32) * KP + hi * 16, lds + OFF_V + cur * VBUF + q32 * VP + sub * 128 + hi * 8, wsf, (2 * it + sub) * 64, qpos, q32, hi);
;         if (var != 2) SM_STORE(cur ^ 1);
;         __syncthreads();
.Lm3_ok4:
	s_add_i32 s19, s19, 1
	s_and_b32 s43, s19, 1
	s_mul_i32 s20, s43, 0x6800
	v_add_u32_e32 v1, s20, v175
	v_lshl_add_u64 v[162:163], v[162:163], 0, s[94:95]
	v_lshl_add_u64 v[164:165], v[164:165], 0, s[96:97]
	v_lshl_add_u64 v[166:167], v[166:167], 0, s[38:39]
	s_cmp_eq_u32 s18, s19
	s_waitcnt lgkmcnt(0)
	s_barrier
	s_cbranch_scc1 .Lm3_drain
	ds_read_b128 v[116:119], v1 offset:0
	ds_read_b128 v[120:123], v1 offset:32
	ds_read_b128 v[124:127], v1 offset:64
	ds_read_b128 v[128:131], v1 offset:96
	ds_read_b128 v[132:135], v1 offset:128
	ds_read_b128 v[136:139], v1 offset:160
	v_lshl_add_u64 v[2:3], s[22:23], 0, v[166:167]
	v_add_co_u32_e32 v4, vcc, 0x104a0000, v2
	v_lshl_add_u64 v[10:11], s[22:23], 0, v[162:163]
	s_nop 0
	v_addc_co_u32_e32 v5, vcc, 0, v3, vcc
	v_add_co_u32_e32 v2, vcc, 0x104c0000, v2
	s_and_b32 s43, s19, 1
	s_nop 0
	v_addc_co_u32_e32 v3, vcc, 0, v3, vcc
	v_add_co_u32_e32 v14, vcc, 0x12460000, v10
	global_load_dwordx4 v[6:9], v[4:5], off
	s_nop 0
	global_load_dwordx4 v[2:5], v[2:3], off
	v_addc_co_u32_e32 v15, vcc, 0, v11, vcc
	global_load_dwordx4 v[10:13], v[14:15], off offset:256
	global_load_dwordx4 v[108:111], v[14:15], off offset:384
	v_lshl_add_u64 v[14:15], s[22:23], 0, v[164:165]
	global_load_dwordx4 v[112:115], v[14:15], off
	s_mul_i32 s20, s43, 0x6800
	v_add_u32_e32 v1, s20, v175
	s_mul_i32 s20, s43, 0x4200
	v_add_u32_e32 v15, s20, v174
	v_add_u32_e32 v14, 0xd000, v15
	v_add_u32_e32 v176, 0xf000, v15
	v_exp_f32_e32 v48, v48
	v_exp_f32_e32 v49, v49
	v_exp_f32_e32 v50, v50
	v_add_f32_e32 v15, v48, v49
	v_exp_f32_e32 v51, v51
	v_cvt_pk_bf16_f32 v214, v48, v49
	v_exp_f32_e32 v52, v52
	v_add_f32_e32 v177, v50, v51
	v_exp_f32_e32 v53, v53
	v_cvt_pk_bf16_f32 v215, v50, v51
	v_exp_f32_e32 v54, v54
	v_add_f32_e32 v15, v15, v52
	v_exp_f32_e32 v55, v55
	v_add_f32_e32 v177, v177, v53
	v_exp_f32_e32 v56, v56
	v_cvt_pk_bf16_f32 v216, v52, v53
	v_exp_f32_e32 v57, v57
	v_add_f32_e32 v15, v15, v54
	v_exp_f32_e32 v58, v58
	v_add_f32_e32 v177, v177, v55
	v_exp_f32_e32 v59, v59
	v_cvt_pk_bf16_f32 v217, v54, v55
	v_exp_f32_e32 v60, v60
	v_add_f32_e32 v15, v15, v56
	v_exp_f32_e32 v61, v61
	v_add_f32_e32 v177, v177, v57
	v_exp_f32_e32 v62, v62
	v_cvt_pk_bf16_f32 v218, v56, v57
	s_waitcnt lgkmcnt(5)
	v_mfma_f32_32x32x16_bf16 v[64:79], v[116:119], v[84:87], v[198:213]
	v_exp_f32_e32 v63, v63
	v_add_f32_e32 v15, v15, v58
	s_waitcnt lgkmcnt(4)
	v_mfma_f32_32x32x16_bf16 v[64:79], v[120:123], v[88:91], v[64:79]
	v_add_f32_e32 v177, v177, v59
	v_cvt_pk_bf16_f32 v219, v58, v59
	s_waitcnt lgkmcnt(3)
	v_mfma_f32_32x32x16_bf16 v[64:79], v[124:127], v[92:95], v[64:79]
	v_add_f32_e32 v15, v15, v60
	v_add_f32_e32 v177, v177, v61
	s_waitcnt lgkmcnt(2)
	v_mfma_f32_32x32x16_bf16 v[64:79], v[128:131], v[96:99], v[64:79]
	v_cvt_pk_bf16_f32 v220, v60, v61
	v_add_f32_e32 v15, v15, v62
	s_waitcnt lgkmcnt(1)
	v_mfma_f32_32x32x16_bf16 v[64:79], v[132:135], v[100:103], v[64:79]
	v_add_f32_e32 v177, v177, v63
	v_cvt_pk_bf16_f32 v221, v62, v63
	s_waitcnt lgkmcnt(0)
	v_mfma_f32_32x32x16_bf16 v[64:79], v[136:139], v[104:107], v[64:79]
	v_add_f32_e32 v15, v15, v177
	v_add_f32_e32 v170, v170, v15
	s_waitcnt lgkmcnt(0)
	ds_read_b128 v[116:119], v1 offset:6656
	ds_read_b128 v[120:123], v1 offset:6688
	ds_read_b128 v[124:127], v1 offset:6720
	ds_read_b128 v[128:131], v1 offset:6752
	ds_read_b128 v[132:135], v1 offset:6784
	ds_read_b128 v[136:139], v1 offset:6816
	v_mfma_f32_32x32x16_bf16 v[16:31], v[214:217], v[140:143], v[16:31]
	ds_read2_b64 v[140:143], v14 offset0:0 offset1:2
	v_mfma_f32_32x32x16_bf16 v[32:47], v[214:217], v[144:147], v[32:47]
	ds_read2_b64 v[144:147], v176 offset0:32 offset1:34
	v_mfma_f32_32x32x16_bf16 v[16:31], v[218:221], v[180:183], v[16:31]
	ds_read2_b64 v[180:183], v14 offset0:4 offset1:6
	v_mfma_f32_32x32x16_bf16 v[32:47], v[218:221], v[184:187], v[32:47]
	ds_read2_b64 v[184:187], v176 offset0:36 offset1:38
	v_max3_f32 v15, v64, v65, v66
	v_max3_f32 v177, v67, v68, v69
	v_max3_f32 v15, v15, v70, v71
	v_max3_f32 v177, v177, v72, v73
	v_max3_f32 v15, v15, v74, v75
	v_max3_f32 v177, v177, v76, v77
	v_max3_f32 v15, v15, v78, v79
	v_max_f32_e32 v15, v15, v177
	v_mov_b32_e32 v177, v15
	v_mov_b32_e32 v178, v15
	s_nop 1
	v_permlane32_swap_b32_e32 v177, v178
	v_max3_f32 v15, v15, v177, v178
	v_cmp_gt_f32_e32 vcc, v15, v197
	s_cbranch_vccz .Lm3_ok5
	v_max_f32_e32 v15, v171, v15
	v_sub_f32_e32 v177, v171, v15
	v_exp_f32_e32 v177, v177
	v_sub_f32_e32 v198, v198, v15
	s_and_saveexec_b64 s[20:21], s[40:41]
	ds_write_b32 v149, v177
	s_or_b64 exec, exec, s[20:21]
	v_mul_f32_e32 v170, v170, v177
	v_add_u32_e32 v178, s25, v148
	s_waitcnt lgkmcnt(0)
	ds_read_b128 v[188:191], v178
	ds_read_b128 v[192:195], v178 offset:32
	ds_read_b128 v[222:225], v178 offset:64
	ds_read_b128 v[236:239], v178 offset:96
	v_sub_f32_e32 v64, v64, v15
	v_sub_f32_e32 v65, v65, v15
	v_sub_f32_e32 v66, v66, v15
	v_sub_f32_e32 v67, v67, v15
	v_sub_f32_e32 v68, v68, v15
	v_sub_f32_e32 v69, v69, v15
	v_sub_f32_e32 v70, v70, v15
	v_sub_f32_e32 v71, v71, v15
	v_sub_f32_e32 v72, v72, v15
	v_sub_f32_e32 v73, v73, v15
	v_sub_f32_e32 v74, v74, v15
	v_sub_f32_e32 v75, v75, v15
	v_sub_f32_e32 v76, v76, v15
	v_sub_f32_e32 v77, v77, v15
	v_sub_f32_e32 v78, v78, v15
	v_sub_f32_e32 v79, v79, v15
	v_mov_b32_e32 v199, v198
	v_mov_b32_e32 v200, v198
	v_mov_b32_e32 v201, v198
	v_mov_b32_e32 v202, v198
	v_mov_b32_e32 v203, v198
	v_mov_b32_e32 v204, v198
	v_mov_b32_e32 v205, v198
	v_mov_b32_e32 v206, v198
	v_mov_b32_e32 v207, v198
	v_mov_b32_e32 v208, v198
	v_mov_b32_e32 v209, v198
	v_mov_b32_e32 v210, v198
	v_mov_b32_e32 v211, v198
	v_mov_b32_e32 v212, v198
	v_mov_b32_e32 v213, v198
	v_mov_b32_e32 v171, 0
	v_mov_b32_e32 v197, 0x41000000
	s_nop 11
	s_nop 3
	s_waitcnt lgkmcnt(0)
	v_pk_mul_f32 v[16:17], v[16:17], v[188:189]
	v_pk_mul_f32 v[32:33], v[32:33], v[188:189]
	v_pk_mul_f32 v[18:19], v[18:19], v[190:191]
	v_pk_mul_f32 v[34:35], v[34:35], v[190:191]
	v_pk_mul_f32 v[20:21], v[20:21], v[192:193]
	v_pk_mul_f32 v[36:37], v[36:37], v[192:193]
	v_pk_mul_f32 v[22:23], v[22:23], v[194:195]
	v_pk_mul_f32 v[38:39], v[38:39], v[194:195]
	v_pk_mul_f32 v[24:25], v[24:25], v[222:223]
	v_pk_mul_f32 v[40:41], v[40:41], v[222:223]
	v_pk_mul_f32 v[26:27], v[26:27], v[224:225]
	v_pk_mul_f32 v[42:43], v[42:43], v[224:225]
	v_pk_mul_f32 v[28:29], v[28:29], v[236:237]
	v_pk_mul_f32 v[44:45], v[44:45], v[236:237]
	v_pk_mul_f32 v[30:31], v[30:31], v[238:239]
	v_pk_mul_f32 v[46:47], v[46:47], v[238:239]
